# GU ssq loads merged + uq rs loads hoisted (on top of previous)
# speedup vs baseline: 1.0027x; 1.0027x over previous
; #define LAS __attribute__((address_space(3)))
; #define GAS __attribute__((address_space(1)))
;     __device__ __forceinline__ void operator()(const f32x4 (&acc)[2][2][4][2], const Unit& u, int wr, int wc, int fr_, int fq_) const {
;     ...
;         float rs[2][4];
; #pragma unroll
;         for (int ai = 0; ai < 2; ++ai)
; #pragma unroll
;             for (int m = 0; m < 4; ++m) rs[ai][m] = rsqrtf((float)*(const GAS u64_t*)(ssq + (size_t)u.pm * BM + ai * HALF + wr * 64 + m * 16 + fr) * (SSQ_INV / DM) + EPS);
; #pragma unroll
;         for (int ai = 0; ai < 2; ++ai) { const int bidx = 2 * ai + wr; LAS float* xb = X + ((bidx * 4 + wc) * 2) * 32 + fq * 8;
;             if (fr == 0) { *(LAS f32x4*)(xb) = acc[ai][0][0][0] * rs[ai][0]; *(LAS f32x4*)(xb + 4) = acc[ai][0][0][1] * rs[ai][0]; }
;             if (fr == 15) { *(LAS f32x4*)(xb + 32) = acc[ai][0][3][0] * rs[ai][3]; *(LAS f32x4*)(xb + 36) = acc[ai][0][3][1] * rs[ai][3]; } }
.LBB0_184:
	s_ashr_i32 s43, s42, 31
	s_lshl_b64 s[0:1], s[42:43], 11
	v_readlane_b32 s38, v254, 63
	v_mov_b32_e32 v172, v210
	v_mov_b32_e32 v43, v211
	s_add_u32 s0, s38, s0
	v_readlane_b32 s38, v255, 0
	s_addc_u32 s1, s38, s1
	v_ashrrev_i32_e32 v173, 31, v172
	v_lshl_add_u64 v[20:21], v[172:173], 3, s[0:1]
	global_load_dwordx2 v[52:53], v[20:21], off
	global_load_dwordx2 v[174:175], v[20:21], off offset:128
	global_load_dwordx2 v[196:197], v[20:21], off offset:256
	global_load_dwordx2 v[176:177], v[20:21], off offset:384
	global_load_dwordx2 v[178:179], v[20:21], off offset:1024
	global_load_dwordx2 v[182:183], v[20:21], off offset:1152
	global_load_dwordx2 v[180:181], v[20:21], off offset:1280
	global_load_dwordx2 v[152:153], v[20:21], off offset:1408
	s_mov_b32 s0, 0x800000
	s_mov_b64 s[38:39], 0
	s_waitcnt vmcnt(0)
	v_ffbh_u32_e32 v42, v53
	v_min_u32_e32 v42, 32, v42
	v_lshlrev_b64 v[52:53], v42, v[52:53]
	v_min_u32_e32 v52, 1, v52
	v_or_b32_e32 v52, v53, v52
	v_cvt_f32_u32_e32 v52, v52
	v_sub_u32_e32 v42, 32, v42
	v_ldexp_f32 v42, v52, v42
	v_mov_b32_e32 v52, v176
	v_mov_b32_e32 v53, v177
	v_fmamk_f32 v78, v42, 0x32000000, v232
	v_cmp_gt_f32_e32 vcc, s0, v78
	v_ffbh_u32_e32 v42, v53
	v_min_u32_e32 v42, 32, v42
	v_lshlrev_b64 v[52:53], v42, v[52:53]
	v_min_u32_e32 v52, 1, v52
	v_or_b32_e32 v52, v53, v52
	v_cvt_f32_u32_e32 v52, v52
	v_sub_u32_e32 v42, 32, v42
	v_ldexp_f32 v42, v52, v42
	v_fmamk_f32 v42, v42, 0x32000000, v232
	v_cmp_gt_f32_e64 s[0:1], s0, v42
	v_mul_f32_e32 v52, 0x4b800000, v42
	s_nop 0
	v_cndmask_b32_e64 v42, v42, v52, s[0:1]
	v_rsq_f32_e32 v42, v42
	s_nop 0
	v_mul_f32_e32 v52, 0x45800000, v42
	v_cndmask_b32_e64 v42, v42, v52, s[0:1]
	v_mov_b32_e32 v52, v178
	v_mov_b32_e32 v53, v179
	s_nop 0
	v_mov_b32_e32 v20, v152
	v_mov_b32_e32 v21, v153
	v_readlane_b32 s0, v255, 1
	s_nop 1
	v_lshl_add_u32 v214, v43, 5, s0
	v_cmp_lt_i32_e64 s[0:1], 14, v172
	s_and_saveexec_b64 s[40:41], s[0:1]
	s_xor_b64 s[40:41], exec, s[40:41]
	s_cbranch_execz .LBB0_188
	v_cmp_eq_u32_e64 s[0:1], 15, v172
	s_and_saveexec_b64 s[44:45], s[0:1]
	s_cbranch_execz .LBB0_187
	v_pk_mul_f32 v[98:99], v[126:127], v[42:43] op_sel_hi:[1,0]
	v_pk_mul_f32 v[96:97], v[124:125], v[42:43] op_sel_hi:[1,0]
	ds_write_b128 v214, v[96:99] offset:128
	v_mov_b64_e32 v[98:99], v[44:45]
	s_mov_b64 s[38:39], exec
	v_mov_b64_e32 v[96:97], v[42:43]

; #define GAS __attribute__((address_space(1)))
; __device__ __forceinline__ unsigned cvt_pk_bf16(float lo, float hi) { unsigned r; asm volatile("v_cvt_pk_bf16_f32 %0, %1, %2" : "=v"(r) : "v"(lo), "v"(hi)); return r; }
;     __device__ __forceinline__ void operator()(const f32x4 (&acc)[2][2][4][2], const Unit& u, int wr, int wc, int fr, int fq) const {
;     ...
;         for (int bj = 0; bj < 2; ++bj) {
;             const int cb = u.pn * BM + bj * HALF + wc * 32, d = cb % 192; const bool rope = d >= 128; const int j0 = ((d - 128) >> 1) + 4 * fq;
; #pragma unroll
;             for (int ai = 0; ai < 2; ++ai)
; #pragma unroll
;                 for (int m = 0; m < 4; ++m) { const int r = row0 + ai * HALF + m * 16; const float s = *(const GAS float*)(rs + r) * 0.10411754831265403f;
;                     f32x4 v0 = acc[ai][bj][m][0] * s, v1 = acc[ai][bj][m][1] * s;
;                     if (rope) { const f32x4 c4 = *(const GAS f32x4*)(cs + (size_t)r * 32 + j0), s4 = *(const GAS f32x4*)(sn + (size_t)r * 32 + j0);
;                         f32x4 a, b; a[0] = v0[0] * c4[0] - v0[1] * s4[0]; a[1] = v0[0] * s4[0] + v0[1] * c4[0]; a[2] = v0[2] * c4[1] - v0[3] * s4[1]; a[3] = v0[2] * s4[1] + v0[3] * c4[1];
;                         b[0] = v1[0] * c4[2] - v1[1] * s4[2]; b[1] = v1[0] * s4[2] + v1[1] * c4[2]; b[2] = v1[2] * c4[3] - v1[3] * s4[3]; b[3] = v1[2] * s4[3] + v1[3] * c4[3]; v0 = a; v1 = b; }
;                     u32x4 w; w.x = cvt_pk_bf16(v0[0], v0[1]); w.y = cvt_pk_bf16(v0[2], v0[3]); w.z = cvt_pk_bf16(v1[0], v1[1]); w.w = cvt_pk_bf16(v1[2], v1[3]);
;                     *(GAS u32x4*)(O + (size_t)r * QW + col0 + bj * HALF) = w; }
.LBB0_543:
	v_lshl_add_u32 v140, s66, 8, v150
	v_ashrrev_i32_e32 v141, 31, v140
	v_lshl_add_u64 v[138:139], v[140:141], 2, s[84:85]
	global_load_dword v144, v[138:139], off
	global_load_dword v192, v[138:139], off
	global_load_dword v193, v[138:139], off offset:64
	global_load_dword v194, v[138:139], off offset:128
	global_load_dword v195, v[138:139], off offset:192
	global_load_dword v196, v[138:139], off offset:512
	global_load_dword v197, v[138:139], off offset:576
	global_load_dword v198, v[138:139], off offset:640
	global_load_dword v199, v[138:139], off offset:704
	s_lshl_b32 s38, s63, 8
	s_or_b32 s63, s38, s55
	s_mul_hi_i32 s39, s63, 0x2aaaaaab
	s_lshr_b32 s50, s39, 31
	s_lshr_b32 s39, s39, 5
	s_add_i32 s39, s39, s50
	s_mulk_i32 s39, 0xc0
	s_sub_i32 s39, s63, s39
	s_cmpk_gt_i32 s39, 0x7f
	s_cselect_b64 s[50:51], -1, 0
	s_add_i32 s66, s39, 0xffffff80
	s_ashr_i32 s66, s66, 1
	v_or_b32_e32 v142, s66, v153
	v_ashrrev_i32_e32 v143, 31, v142
	s_cmpk_lt_i32 s39, 0x80
	s_waitcnt vmcnt(0)
	v_mul_f32_e32 v156, 0x3dd53b95, v144
	v_pk_mul_f32 v[146:147], v[122:123], v[156:157] op_sel_hi:[1,0]
	v_lshlrev_b64 v[122:123], 7, v[140:141]
	v_pk_mul_f32 v[148:149], v[126:127], v[156:157] op_sel_hi:[1,0]
	v_pk_mul_f32 v[144:145], v[124:125], v[156:157] op_sel_hi:[1,0]
	v_pk_mul_f32 v[124:125], v[120:121], v[156:157] op_sel_hi:[1,0]
	v_lshlrev_b64 v[126:127], 2, v[142:143]
	v_lshl_add_u64 v[120:121], s[16:17], 0, v[122:123]
	v_lshl_add_u64 v[122:123], s[18:19], 0, v[122:123]
	s_cbranch_scc1 .LBB0_545
	v_lshl_add_u64 v[142:143], v[120:121], 0, v[126:127]
	global_load_dwordx4 v[156:159], v[142:143], off
	v_lshl_add_u64 v[142:143], v[122:123], 0, v[126:127]
	global_load_dwordx4 v[160:163], v[142:143], off
	s_waitcnt vmcnt(0)
	v_pk_mul_f32 v[164:165], v[144:145], v[156:157]
	v_pk_mul_f32 v[142:143], v[144:145], v[160:161] op_sel:[1,0] op_sel_hi:[0,0]
	v_pk_fma_f32 v[144:145], v[144:145], v[156:157], v[142:143] op_sel_hi:[1,0,1]
	v_mov_b32_e32 v160, v157
	v_mul_f32_e32 v144, v149, v161
	v_pk_fma_f32 v[166:167], v[148:149], v[160:161], v[144:145] op_sel_hi:[1,1,0] neg_lo:[0,0,1] neg_hi:[0,0,1]
	v_mov_b32_e32 v156, v161
	v_mul_f32_e32 v144, v149, v157
	v_pk_fma_f32 v[156:157], v[148:149], v[156:157], v[144:145] op_sel_hi:[1,1,0]
	v_pk_mul_f32 v[148:149], v[124:125], v[162:163] op_sel:[1,0] op_sel_hi:[0,0]
	v_pk_mul_f32 v[160:161], v[124:125], v[158:159]
	v_pk_fma_f32 v[124:125], v[124:125], v[158:159], v[148:149] op_sel_hi:[1,0,1]
	v_mov_b32_e32 v162, v159
	v_mul_f32_e32 v124, v147, v163
	v_pk_fma_f32 v[168:169], v[146:147], v[162:163], v[124:125] op_sel_hi:[1,1,0] neg_lo:[0,0,1] neg_hi:[0,0,1]
	v_mov_b32_e32 v158, v163
	v_mul_f32_e32 v124, v147, v159
	v_pk_fma_f32 v[158:159], v[146:147], v[158:159], v[124:125] op_sel_hi:[1,1,0]
	v_sub_f32_e32 v144, v164, v142
	v_sub_f32_e32 v124, v160, v148
	v_mov_b32_e32 v148, v166
	v_mov_b32_e32 v149, v156
	v_mov_b32_e32 v146, v168
	v_mov_b32_e32 v147, v158
.LBB0_545:
	v_or_b32_e32 v142, s38, v152
	v_cvt_pk_bf16_f32 v156, v144, v145
	v_cvt_pk_bf16_f32 v157, v148, v149
	v_cvt_pk_bf16_f32 v158, v124, v125
	v_mov_b64_e32 v[124:125], s[46:47]
	s_movk_i32 s38, 0xc00
	v_ashrrev_i32_e32 v143, 31, v142
	v_mad_i64_i32 v[124:125], s[38:39], v140, s38, v[124:125]
	v_lshl_add_u64 v[124:125], v[142:143], 1, v[124:125]
	v_cvt_pk_bf16_f32 v159, v146, v147
	global_store_dwordx4 v[124:125], v[156:159], off
	v_mov_b32_e32 v141, v193
	v_or_b32_e32 v144, 16, v140
	v_ashrrev_i32_e32 v145, 31, v144
	s_andn2_b64 vcc, exec, s[50:51]
	v_mul_f32_e32 v156, 0x3dd53b95, v141
	v_pk_mul_f32 v[148:149], v[118:119], v[156:157] op_sel_hi:[1,0]
	v_pk_mul_f32 v[118:119], v[116:117], v[156:157] op_sel_hi:[1,0]
	v_pk_mul_f32 v[146:147], v[114:115], v[156:157] op_sel_hi:[1,0]
	v_pk_mul_f32 v[116:117], v[112:113], v[156:157] op_sel_hi:[1,0]
	v_cndmask_b32_e64 v112, 0, 1, s[50:51]
	v_lshlrev_b64 v[114:115], 7, v[144:145]
	v_cmp_ne_u32_e64 s[38:39], 1, v112
	v_lshl_add_u64 v[112:113], s[16:17], 0, v[114:115]
	v_lshl_add_u64 v[114:115], s[18:19], 0, v[114:115]
	s_cbranch_vccnz .LBB0_547
	v_lshl_add_u64 v[156:157], v[112:113], 0, v[126:127]
	v_lshl_add_u64 v[160:161], v[114:115], 0, v[126:127]
	global_load_dwordx4 v[156:159], v[156:157], off
	s_nop 0
	global_load_dwordx4 v[160:163], v[160:161], off
	s_waitcnt vmcnt(0)
	v_pk_mul_f32 v[166:167], v[118:119], v[156:157]
	v_pk_mul_f32 v[164:165], v[118:119], v[160:161] op_sel:[1,0] op_sel_hi:[0,0]
	v_pk_fma_f32 v[118:119], v[118:119], v[156:157], v[164:165] op_sel_hi:[1,0,1]
	v_mov_b32_e32 v160, v157
	v_mul_f32_e32 v118, v149, v161
	v_pk_fma_f32 v[168:169], v[148:149], v[160:161], v[118:119] op_sel_hi:[1,1,0] neg_lo:[0,0,1] neg_hi:[0,0,1]
	v_mov_b32_e32 v156, v161
	v_mul_f32_e32 v118, v149, v157
	v_pk_fma_f32 v[156:157], v[148:149], v[156:157], v[118:119] op_sel_hi:[1,1,0]
	v_pk_mul_f32 v[148:149], v[116:117], v[162:163] op_sel:[1,0] op_sel_hi:[0,0]
	v_pk_mul_f32 v[160:161], v[116:117], v[158:159]
	v_pk_fma_f32 v[116:117], v[116:117], v[158:159], v[148:149] op_sel_hi:[1,0,1]
	v_mov_b32_e32 v162, v159
	v_mul_f32_e32 v116, v147, v163
	v_pk_fma_f32 v[170:171], v[146:147], v[162:163], v[116:117] op_sel_hi:[1,1,0] neg_lo:[0,0,1] neg_hi:[0,0,1]
	v_mov_b32_e32 v158, v163
	v_mul_f32_e32 v116, v147, v159
	v_pk_fma_f32 v[158:159], v[146:147], v[158:159], v[116:117] op_sel_hi:[1,1,0]
	v_sub_f32_e32 v118, v166, v164
	v_sub_f32_e32 v116, v160, v148
	v_mov_b32_e32 v148, v168
	v_mov_b32_e32 v149, v156
	v_mov_b32_e32 v146, v170
	v_mov_b32_e32 v147, v158
; #define GAS __attribute__((address_space(1)))
; __device__ __forceinline__ unsigned cvt_pk_bf16(float lo, float hi) { unsigned r; asm volatile("v_cvt_pk_bf16_f32 %0, %1, %2" : "=v"(r) : "v"(lo), "v"(hi)); return r; }
;     __device__ __forceinline__ void operator()(const f32x4 (&acc)[2][2][4][2], const Unit& u, int wr, int wc, int fr, int fq) const {
;     ...
;                 for (int m = 0; m < 4; ++m) { const int r = row0 + ai * HALF + m * 16; const float s = *(const GAS float*)(rs + r) * 0.10411754831265403f;
;                     f32x4 v0 = acc[ai][bj][m][0] * s, v1 = acc[ai][bj][m][1] * s;
;                     if (rope) { const f32x4 c4 = *(const GAS f32x4*)(cs + (size_t)r * 32 + j0), s4 = *(const GAS f32x4*)(sn + (size_t)r * 32 + j0);
;                         f32x4 a, b; a[0] = v0[0] * c4[0] - v0[1] * s4[0]; a[1] = v0[0] * s4[0] + v0[1] * c4[0]; a[2] = v0[2] * c4[1] - v0[3] * s4[1]; a[3] = v0[2] * s4[1] + v0[3] * c4[1];
;                         b[0] = v1[0] * c4[2] - v1[1] * s4[2]; b[1] = v1[0] * s4[2] + v1[1] * c4[2]; b[2] = v1[2] * c4[3] - v1[3] * s4[3]; b[3] = v1[2] * s4[3] + v1[3] * c4[3]; v0 = a; v1 = b; }
;                     u32x4 w; w.x = cvt_pk_bf16(v0[0], v0[1]); w.y = cvt_pk_bf16(v0[2], v0[3]); w.z = cvt_pk_bf16(v1[0], v1[1]); w.w = cvt_pk_bf16(v1[2], v1[3]);
;                     *(GAS u32x4*)(O + (size_t)r * QW + col0 + bj * HALF) = w; }
.LBB0_547:
	v_cvt_pk_bf16_f32 v156, v118, v119
	v_cvt_pk_bf16_f32 v157, v148, v149
	v_cvt_pk_bf16_f32 v158, v116, v117
	v_mov_b64_e32 v[116:117], s[46:47]
	s_movk_i32 s42, 0xc00
	v_mad_i64_i32 v[116:117], s[50:51], v144, s42, v[116:117]
	v_lshl_add_u64 v[118:119], v[142:143], 1, v[116:117]
	v_cvt_pk_bf16_f32 v159, v146, v147
	global_store_dwordx4 v[118:119], v[156:159], off
	v_mov_b32_e32 v141, v194
	v_or_b32_e32 v144, 32, v140
	v_ashrrev_i32_e32 v145, 31, v144
	v_lshlrev_b64 v[148:149], 7, v[144:145]
	s_and_b64 vcc, exec, s[38:39]
	v_lshl_add_u64 v[116:117], s[16:17], 0, v[148:149]
	v_mul_f32_e32 v156, 0x3dd53b95, v141
	v_pk_mul_f32 v[146:147], v[110:111], v[156:157] op_sel_hi:[1,0]
	v_pk_mul_f32 v[108:109], v[108:109], v[156:157] op_sel_hi:[1,0]
	v_pk_mul_f32 v[110:111], v[106:107], v[156:157] op_sel_hi:[1,0]
	v_pk_mul_f32 v[106:107], v[104:105], v[156:157] op_sel_hi:[1,0]
	v_lshl_add_u64 v[104:105], s[18:19], 0, v[148:149]
	s_cbranch_vccnz .LBB0_549
	v_lshl_add_u64 v[148:149], v[116:117], 0, v[126:127]
	global_load_dwordx4 v[156:159], v[148:149], off
	v_lshl_add_u64 v[148:149], v[104:105], 0, v[126:127]
	global_load_dwordx4 v[160:163], v[148:149], off
	s_waitcnt vmcnt(0)
	v_pk_mul_f32 v[164:165], v[108:109], v[156:157]
	v_pk_mul_f32 v[148:149], v[108:109], v[160:161] op_sel:[1,0] op_sel_hi:[0,0]
	v_pk_fma_f32 v[108:109], v[108:109], v[156:157], v[148:149] op_sel_hi:[1,0,1]
	v_mov_b32_e32 v160, v157
	v_mul_f32_e32 v108, v147, v161
	v_pk_fma_f32 v[166:167], v[146:147], v[160:161], v[108:109] op_sel_hi:[1,1,0] neg_lo:[0,0,1] neg_hi:[0,0,1]
	v_mov_b32_e32 v156, v161
	v_mul_f32_e32 v108, v147, v157
	v_pk_fma_f32 v[156:157], v[146:147], v[156:157], v[108:109] op_sel_hi:[1,1,0]
	v_pk_mul_f32 v[146:147], v[106:107], v[162:163] op_sel:[1,0] op_sel_hi:[0,0]
	v_pk_mul_f32 v[160:161], v[106:107], v[158:159]
	v_pk_fma_f32 v[106:107], v[106:107], v[158:159], v[146:147] op_sel_hi:[1,0,1]
	v_mov_b32_e32 v162, v159
	v_mul_f32_e32 v106, v111, v163
	v_pk_fma_f32 v[168:169], v[110:111], v[162:163], v[106:107] op_sel_hi:[1,1,0] neg_lo:[0,0,1] neg_hi:[0,0,1]
	v_mov_b32_e32 v158, v163
	v_mul_f32_e32 v106, v111, v159
	v_pk_fma_f32 v[158:159], v[110:111], v[158:159], v[106:107] op_sel_hi:[1,1,0]
	v_sub_f32_e32 v108, v164, v148
	v_sub_f32_e32 v106, v160, v146
	v_mov_b32_e32 v146, v166
	v_mov_b32_e32 v147, v156
	v_mov_b32_e32 v110, v168
	v_mov_b32_e32 v111, v158
.LBB0_549:
	v_cvt_pk_bf16_f32 v156, v108, v109
	v_cvt_pk_bf16_f32 v157, v146, v147
	v_cvt_pk_bf16_f32 v158, v106, v107
	v_mov_b64_e32 v[106:107], s[46:47]
	v_mad_i64_i32 v[106:107], s[50:51], v144, s42, v[106:107]
	v_lshl_add_u64 v[108:109], v[142:143], 1, v[106:107]
	v_cvt_pk_bf16_f32 v159, v110, v111
	global_store_dwordx4 v[108:109], v[156:159], off
	v_mov_b32_e32 v141, v195
	v_or_b32_e32 v110, 48, v140
	v_ashrrev_i32_e32 v111, 31, v110
	v_lshlrev_b64 v[146:147], 7, v[110:111]
	s_and_b64 vcc, exec, s[38:39]
	v_lshl_add_u64 v[106:107], s[16:17], 0, v[146:147]
	v_mul_f32_e32 v148, 0x3dd53b95, v141
	v_pk_mul_f32 v[144:145], v[102:103], v[148:149] op_sel_hi:[1,0]
	v_pk_mul_f32 v[100:101], v[100:101], v[148:149] op_sel_hi:[1,0]
	v_pk_mul_f32 v[102:103], v[98:99], v[148:149] op_sel_hi:[1,0]
	v_pk_mul_f32 v[98:99], v[96:97], v[148:149] op_sel_hi:[1,0]
	v_lshl_add_u64 v[96:97], s[18:19], 0, v[146:147]
	s_cbranch_vccnz .LBB0_551
	v_lshl_add_u64 v[146:147], v[106:107], 0, v[126:127]
	v_lshl_add_u64 v[156:157], v[96:97], 0, v[126:127]
	global_load_dwordx4 v[146:149], v[146:147], off
	s_nop 0
	global_load_dwordx4 v[156:159], v[156:157], off
	s_waitcnt vmcnt(0)
	v_pk_mul_f32 v[162:163], v[100:101], v[146:147]
	v_pk_mul_f32 v[160:161], v[100:101], v[156:157] op_sel:[1,0] op_sel_hi:[0,0]
	v_pk_fma_f32 v[100:101], v[100:101], v[146:147], v[160:161] op_sel_hi:[1,0,1]
	v_mov_b32_e32 v156, v147
	v_mul_f32_e32 v100, v145, v157
	v_pk_fma_f32 v[164:165], v[144:145], v[156:157], v[100:101] op_sel_hi:[1,1,0] neg_lo:[0,0,1] neg_hi:[0,0,1]
	v_mov_b32_e32 v146, v157
	v_mul_f32_e32 v100, v145, v147
	v_pk_fma_f32 v[146:147], v[144:145], v[146:147], v[100:101] op_sel_hi:[1,1,0]
	v_pk_mul_f32 v[144:145], v[98:99], v[158:159] op_sel:[1,0] op_sel_hi:[0,0]
	v_pk_mul_f32 v[156:157], v[98:99], v[148:149]
	v_pk_fma_f32 v[98:99], v[98:99], v[148:149], v[144:145] op_sel_hi:[1,0,1]
	v_mov_b32_e32 v158, v149
	v_mul_f32_e32 v98, v103, v159
	v_pk_fma_f32 v[166:167], v[102:103], v[158:159], v[98:99] op_sel_hi:[1,1,0] neg_lo:[0,0,1] neg_hi:[0,0,1]
	v_mov_b32_e32 v148, v159
	v_mul_f32_e32 v98, v103, v149
	v_pk_fma_f32 v[148:149], v[102:103], v[148:149], v[98:99] op_sel_hi:[1,1,0]
	v_sub_f32_e32 v100, v162, v160
	v_sub_f32_e32 v98, v156, v144
	v_mov_b32_e32 v144, v164
	v_mov_b32_e32 v145, v146
	v_mov_b32_e32 v102, v166
	v_mov_b32_e32 v103, v148
; #define GAS __attribute__((address_space(1)))
; __device__ __forceinline__ unsigned cvt_pk_bf16(float lo, float hi) { unsigned r; asm volatile("v_cvt_pk_bf16_f32 %0, %1, %2" : "=v"(r) : "v"(lo), "v"(hi)); return r; }
;     __device__ __forceinline__ void operator()(const f32x4 (&acc)[2][2][4][2], const Unit& u, int wr, int wc, int fr, int fq) const {
;     ...
;                 for (int m = 0; m < 4; ++m) { const int r = row0 + ai * HALF + m * 16; const float s = *(const GAS float*)(rs + r) * 0.10411754831265403f;
;                     f32x4 v0 = acc[ai][bj][m][0] * s, v1 = acc[ai][bj][m][1] * s;
;                     if (rope) { const f32x4 c4 = *(const GAS f32x4*)(cs + (size_t)r * 32 + j0), s4 = *(const GAS f32x4*)(sn + (size_t)r * 32 + j0);
;                         f32x4 a, b; a[0] = v0[0] * c4[0] - v0[1] * s4[0]; a[1] = v0[0] * s4[0] + v0[1] * c4[0]; a[2] = v0[2] * c4[1] - v0[3] * s4[1]; a[3] = v0[2] * s4[1] + v0[3] * c4[1];
;                         b[0] = v1[0] * c4[2] - v1[1] * s4[2]; b[1] = v1[0] * s4[2] + v1[1] * c4[2]; b[2] = v1[2] * c4[3] - v1[3] * s4[3]; b[3] = v1[2] * s4[3] + v1[3] * c4[3]; v0 = a; v1 = b; }
;                     u32x4 w; w.x = cvt_pk_bf16(v0[0], v0[1]); w.y = cvt_pk_bf16(v0[2], v0[3]); w.z = cvt_pk_bf16(v1[0], v1[1]); w.w = cvt_pk_bf16(v1[2], v1[3]);
;                     *(GAS u32x4*)(O + (size_t)r * QW + col0 + bj * HALF) = w; }
.LBB0_551:
	v_cvt_pk_bf16_f32 v146, v100, v101
	v_cvt_pk_bf16_f32 v147, v144, v145
	v_cvt_pk_bf16_f32 v148, v98, v99
	v_mov_b64_e32 v[98:99], s[46:47]
	v_mad_i64_i32 v[98:99], s[50:51], v110, s42, v[98:99]
	v_lshl_add_u64 v[100:101], v[142:143], 1, v[98:99]
	v_cvt_pk_bf16_f32 v149, v102, v103
	global_store_dwordx4 v[100:101], v[146:149], off
	v_mov_b32_e32 v110, v196
	v_add_u32_e32 v102, 0x80, v140
	v_ashrrev_i32_e32 v103, 31, v102
	v_lshlrev_b64 v[144:145], 7, v[102:103]
	s_and_b64 vcc, exec, s[38:39]
	v_lshl_add_u64 v[98:99], s[16:17], 0, v[144:145]
	v_mul_f32_e32 v146, 0x3dd53b95, v110
	v_pk_mul_f32 v[110:111], v[94:95], v[146:147] op_sel_hi:[1,0]
	v_pk_mul_f32 v[92:93], v[92:93], v[146:147] op_sel_hi:[1,0]
	v_pk_mul_f32 v[94:95], v[90:91], v[146:147] op_sel_hi:[1,0]
	v_pk_mul_f32 v[90:91], v[88:89], v[146:147] op_sel_hi:[1,0]
	v_lshl_add_u64 v[88:89], s[18:19], 0, v[144:145]
	s_cbranch_vccnz .LBB0_553
	v_lshl_add_u64 v[144:145], v[98:99], 0, v[126:127]
	v_lshl_add_u64 v[148:149], v[88:89], 0, v[126:127]
	global_load_dwordx4 v[144:147], v[144:145], off
	s_nop 0
	global_load_dwordx4 v[156:159], v[148:149], off
	s_waitcnt vmcnt(0)
	v_pk_mul_f32 v[160:161], v[92:93], v[144:145]
	v_pk_mul_f32 v[148:149], v[92:93], v[156:157] op_sel:[1,0] op_sel_hi:[0,0]
	v_pk_fma_f32 v[92:93], v[92:93], v[144:145], v[148:149] op_sel_hi:[1,0,1]
	v_mov_b32_e32 v156, v145
	v_mul_f32_e32 v92, v111, v157
	v_pk_fma_f32 v[162:163], v[110:111], v[156:157], v[92:93] op_sel_hi:[1,1,0] neg_lo:[0,0,1] neg_hi:[0,0,1]
	v_mov_b32_e32 v144, v157
	v_mul_f32_e32 v92, v111, v145
	v_pk_fma_f32 v[144:145], v[110:111], v[144:145], v[92:93] op_sel_hi:[1,1,0]
	v_pk_mul_f32 v[110:111], v[90:91], v[158:159] op_sel:[1,0] op_sel_hi:[0,0]
	v_pk_mul_f32 v[156:157], v[90:91], v[146:147]
	v_pk_fma_f32 v[90:91], v[90:91], v[146:147], v[110:111] op_sel_hi:[1,0,1]
	v_mov_b32_e32 v158, v147
	v_mul_f32_e32 v90, v95, v159
	v_pk_fma_f32 v[164:165], v[94:95], v[158:159], v[90:91] op_sel_hi:[1,1,0] neg_lo:[0,0,1] neg_hi:[0,0,1]
	v_mov_b32_e32 v146, v159
	v_mul_f32_e32 v90, v95, v147
	v_pk_fma_f32 v[146:147], v[94:95], v[146:147], v[90:91] op_sel_hi:[1,1,0]
	v_sub_f32_e32 v92, v160, v148
	v_sub_f32_e32 v90, v156, v110
	v_mov_b32_e32 v110, v162
	v_mov_b32_e32 v111, v144
	v_mov_b32_e32 v94, v164
	v_mov_b32_e32 v95, v146
.LBB0_553:
	v_cvt_pk_bf16_f32 v144, v92, v93
	v_cvt_pk_bf16_f32 v145, v110, v111
	v_cvt_pk_bf16_f32 v146, v90, v91
	v_mov_b64_e32 v[90:91], s[46:47]
	v_mad_i64_i32 v[90:91], s[50:51], v102, s42, v[90:91]
	v_lshl_add_u64 v[92:93], v[142:143], 1, v[90:91]
	v_cvt_pk_bf16_f32 v147, v94, v95
	global_store_dwordx4 v[92:93], v[144:147], off
	v_mov_b32_e32 v102, v197
	v_add_u32_e32 v94, 0x90, v140
	v_ashrrev_i32_e32 v95, 31, v94
	v_lshlrev_b64 v[110:111], 7, v[94:95]
	s_and_b64 vcc, exec, s[38:39]
	v_lshl_add_u64 v[90:91], s[16:17], 0, v[110:111]
	v_mul_f32_e32 v144, 0x3dd53b95, v102
	v_pk_mul_f32 v[102:103], v[86:87], v[144:145] op_sel_hi:[1,0]
	v_pk_mul_f32 v[84:85], v[84:85], v[144:145] op_sel_hi:[1,0]
	v_pk_mul_f32 v[86:87], v[82:83], v[144:145] op_sel_hi:[1,0]
	v_pk_mul_f32 v[82:83], v[80:81], v[144:145] op_sel_hi:[1,0]
	v_lshl_add_u64 v[80:81], s[18:19], 0, v[110:111]
	s_cbranch_vccnz .LBB0_555
	v_lshl_add_u64 v[110:111], v[90:91], 0, v[126:127]
	global_load_dwordx4 v[144:147], v[110:111], off
	v_lshl_add_u64 v[110:111], v[80:81], 0, v[126:127]
	global_load_dwordx4 v[156:159], v[110:111], off
	s_waitcnt vmcnt(0)
	v_pk_mul_f32 v[148:149], v[84:85], v[144:145]
	v_pk_mul_f32 v[110:111], v[84:85], v[156:157] op_sel:[1,0] op_sel_hi:[0,0]
	v_pk_fma_f32 v[84:85], v[84:85], v[144:145], v[110:111] op_sel_hi:[1,0,1]
	v_mov_b32_e32 v156, v145
	v_mul_f32_e32 v84, v103, v157
	v_pk_fma_f32 v[160:161], v[102:103], v[156:157], v[84:85] op_sel_hi:[1,1,0] neg_lo:[0,0,1] neg_hi:[0,0,1]
	v_mov_b32_e32 v144, v157
	v_mul_f32_e32 v84, v103, v145
	v_pk_fma_f32 v[144:145], v[102:103], v[144:145], v[84:85] op_sel_hi:[1,1,0]
	v_pk_mul_f32 v[102:103], v[82:83], v[158:159] op_sel:[1,0] op_sel_hi:[0,0]
	v_pk_mul_f32 v[156:157], v[82:83], v[146:147]
	v_pk_fma_f32 v[82:83], v[82:83], v[146:147], v[102:103] op_sel_hi:[1,0,1]
	v_mov_b32_e32 v158, v147
	v_mul_f32_e32 v82, v87, v159
	v_pk_fma_f32 v[162:163], v[86:87], v[158:159], v[82:83] op_sel_hi:[1,1,0] neg_lo:[0,0,1] neg_hi:[0,0,1]
	v_mov_b32_e32 v146, v159
	v_mul_f32_e32 v82, v87, v147
	v_pk_fma_f32 v[146:147], v[86:87], v[146:147], v[82:83] op_sel_hi:[1,1,0]
	v_sub_f32_e32 v84, v148, v110
	v_sub_f32_e32 v82, v156, v102
	v_mov_b32_e32 v102, v160
	v_mov_b32_e32 v103, v144
	v_mov_b32_e32 v86, v162
	v_mov_b32_e32 v87, v146
; #define GAS __attribute__((address_space(1)))
; __device__ __forceinline__ unsigned cvt_pk_bf16(float lo, float hi) { unsigned r; asm volatile("v_cvt_pk_bf16_f32 %0, %1, %2" : "=v"(r) : "v"(lo), "v"(hi)); return r; }
;     __device__ __forceinline__ void operator()(const f32x4 (&acc)[2][2][4][2], const Unit& u, int wr, int wc, int fr, int fq) const {
;     ...
;                 for (int m = 0; m < 4; ++m) { const int r = row0 + ai * HALF + m * 16; const float s = *(const GAS float*)(rs + r) * 0.10411754831265403f;
;                     f32x4 v0 = acc[ai][bj][m][0] * s, v1 = acc[ai][bj][m][1] * s;
;                     if (rope) { const f32x4 c4 = *(const GAS f32x4*)(cs + (size_t)r * 32 + j0), s4 = *(const GAS f32x4*)(sn + (size_t)r * 32 + j0);
;                         f32x4 a, b; a[0] = v0[0] * c4[0] - v0[1] * s4[0]; a[1] = v0[0] * s4[0] + v0[1] * c4[0]; a[2] = v0[2] * c4[1] - v0[3] * s4[1]; a[3] = v0[2] * s4[1] + v0[3] * c4[1];
;                         b[0] = v1[0] * c4[2] - v1[1] * s4[2]; b[1] = v1[0] * s4[2] + v1[1] * c4[2]; b[2] = v1[2] * c4[3] - v1[3] * s4[3]; b[3] = v1[2] * s4[3] + v1[3] * c4[3]; v0 = a; v1 = b; }
;                     u32x4 w; w.x = cvt_pk_bf16(v0[0], v0[1]); w.y = cvt_pk_bf16(v0[2], v0[3]); w.z = cvt_pk_bf16(v1[0], v1[1]); w.w = cvt_pk_bf16(v1[2], v1[3]);
;                     *(GAS u32x4*)(O + (size_t)r * QW + col0 + bj * HALF) = w; }
.LBB0_555:
	v_cvt_pk_bf16_f32 v144, v84, v85
	v_cvt_pk_bf16_f32 v145, v102, v103
	v_cvt_pk_bf16_f32 v146, v82, v83
	v_mov_b64_e32 v[82:83], s[46:47]
	v_mad_i64_i32 v[82:83], s[50:51], v94, s42, v[82:83]
	v_lshl_add_u64 v[84:85], v[142:143], 1, v[82:83]
	v_cvt_pk_bf16_f32 v147, v86, v87
	global_store_dwordx4 v[84:85], v[144:147], off
	v_mov_b32_e32 v94, v198
	v_add_u32_e32 v86, 0xa0, v140
	v_ashrrev_i32_e32 v87, 31, v86
	v_lshlrev_b64 v[102:103], 7, v[86:87]
	s_and_b64 vcc, exec, s[38:39]
	v_lshl_add_u64 v[82:83], s[16:17], 0, v[102:103]
	v_mul_f32_e32 v110, 0x3dd53b95, v94
	v_pk_mul_f32 v[94:95], v[78:79], v[110:111] op_sel_hi:[1,0]
	v_pk_mul_f32 v[76:77], v[76:77], v[110:111] op_sel_hi:[1,0]
	v_pk_mul_f32 v[78:79], v[74:75], v[110:111] op_sel_hi:[1,0]
	v_pk_mul_f32 v[74:75], v[72:73], v[110:111] op_sel_hi:[1,0]
	v_lshl_add_u64 v[72:73], s[18:19], 0, v[102:103]
	s_cbranch_vccnz .LBB0_557
	v_lshl_add_u64 v[102:103], v[82:83], 0, v[126:127]
	global_load_dwordx4 v[144:147], v[102:103], off
	v_lshl_add_u64 v[102:103], v[72:73], 0, v[126:127]
	global_load_dwordx4 v[156:159], v[102:103], off
	s_waitcnt vmcnt(0)
	v_pk_mul_f32 v[110:111], v[76:77], v[144:145]
	v_pk_mul_f32 v[102:103], v[76:77], v[156:157] op_sel:[1,0] op_sel_hi:[0,0]
	v_pk_fma_f32 v[76:77], v[76:77], v[144:145], v[102:103] op_sel_hi:[1,0,1]
	v_mov_b32_e32 v156, v145
	v_mul_f32_e32 v76, v95, v157
	v_pk_fma_f32 v[148:149], v[94:95], v[156:157], v[76:77] op_sel_hi:[1,1,0] neg_lo:[0,0,1] neg_hi:[0,0,1]
	v_mov_b32_e32 v144, v157
	v_mul_f32_e32 v76, v95, v145
	v_pk_fma_f32 v[144:145], v[94:95], v[144:145], v[76:77] op_sel_hi:[1,1,0]
	v_pk_mul_f32 v[94:95], v[74:75], v[158:159] op_sel:[1,0] op_sel_hi:[0,0]
	v_pk_mul_f32 v[156:157], v[74:75], v[146:147]
	v_pk_fma_f32 v[74:75], v[74:75], v[146:147], v[94:95] op_sel_hi:[1,0,1]
	v_mov_b32_e32 v158, v147
	v_mul_f32_e32 v74, v79, v159
	v_pk_fma_f32 v[160:161], v[78:79], v[158:159], v[74:75] op_sel_hi:[1,1,0] neg_lo:[0,0,1] neg_hi:[0,0,1]
	v_mov_b32_e32 v146, v159
	v_mul_f32_e32 v74, v79, v147
	v_pk_fma_f32 v[146:147], v[78:79], v[146:147], v[74:75] op_sel_hi:[1,1,0]
	v_sub_f32_e32 v76, v110, v102
	v_sub_f32_e32 v74, v156, v94
	v_mov_b32_e32 v94, v148
	v_mov_b32_e32 v95, v144
	v_mov_b32_e32 v78, v160
	v_mov_b32_e32 v79, v146
.LBB0_557:
	v_cvt_pk_bf16_f32 v144, v76, v77
	v_cvt_pk_bf16_f32 v145, v94, v95
	v_cvt_pk_bf16_f32 v146, v74, v75
	v_mov_b64_e32 v[74:75], s[46:47]
	v_mad_i64_i32 v[74:75], s[50:51], v86, s42, v[74:75]
	v_lshl_add_u64 v[76:77], v[142:143], 1, v[74:75]
	v_cvt_pk_bf16_f32 v147, v78, v79
	global_store_dwordx4 v[76:77], v[144:147], off
	v_mov_b32_e32 v86, v199
	v_add_u32_e32 v78, 0xb0, v140
	v_ashrrev_i32_e32 v79, 31, v78
	v_lshlrev_b64 v[94:95], 7, v[78:79]
	s_and_b64 vcc, exec, s[38:39]
	v_lshl_add_u64 v[74:75], s[16:17], 0, v[94:95]
	v_mul_f32_e32 v102, 0x3dd53b95, v86
	v_pk_mul_f32 v[86:87], v[70:71], v[102:103] op_sel_hi:[1,0]
	v_pk_mul_f32 v[68:69], v[68:69], v[102:103] op_sel_hi:[1,0]
	v_pk_mul_f32 v[70:71], v[66:67], v[102:103] op_sel_hi:[1,0]
	v_pk_mul_f32 v[66:67], v[64:65], v[102:103] op_sel_hi:[1,0]
	v_lshl_add_u64 v[64:65], s[18:19], 0, v[94:95]
	s_cbranch_vccnz .LBB0_559
	v_lshl_add_u64 v[94:95], v[74:75], 0, v[126:127]
	global_load_dwordx4 v[144:147], v[94:95], off
	v_lshl_add_u64 v[94:95], v[64:65], 0, v[126:127]
	global_load_dwordx4 v[156:159], v[94:95], off
	s_waitcnt vmcnt(0)
	v_pk_mul_f32 v[102:103], v[68:69], v[144:145]
	v_pk_mul_f32 v[140:141], v[66:67], v[146:147]
	v_pk_mul_f32 v[94:95], v[68:69], v[156:157] op_sel:[1,0] op_sel_hi:[0,0]
	v_pk_fma_f32 v[68:69], v[68:69], v[144:145], v[94:95] op_sel_hi:[1,0,1]
	v_mov_b32_e32 v156, v145
	v_mul_f32_e32 v68, v87, v157
	v_pk_fma_f32 v[110:111], v[86:87], v[156:157], v[68:69] op_sel_hi:[1,1,0] neg_lo:[0,0,1] neg_hi:[0,0,1]
	v_mov_b32_e32 v144, v157
	v_mul_f32_e32 v68, v87, v145
	v_pk_fma_f32 v[126:127], v[86:87], v[144:145], v[68:69] op_sel_hi:[1,1,0]
	v_pk_mul_f32 v[86:87], v[66:67], v[158:159] op_sel:[1,0] op_sel_hi:[0,0]
	v_pk_fma_f32 v[66:67], v[66:67], v[146:147], v[86:87] op_sel_hi:[1,0,1]
	v_mov_b32_e32 v158, v147
	v_mul_f32_e32 v66, v71, v159
	v_pk_fma_f32 v[144:145], v[70:71], v[158:159], v[66:67] op_sel_hi:[1,1,0] neg_lo:[0,0,1] neg_hi:[0,0,1]
	v_mov_b32_e32 v146, v159
	v_mul_f32_e32 v66, v71, v147
	v_pk_fma_f32 v[146:147], v[70:71], v[146:147], v[66:67] op_sel_hi:[1,1,0]
	v_sub_f32_e32 v68, v102, v94
	v_sub_f32_e32 v66, v140, v86
	v_mov_b32_e32 v86, v110
	v_mov_b32_e32 v87, v126
	v_mov_b32_e32 v70, v144
	v_mov_b32_e32 v71, v146
; #define GAS __attribute__((address_space(1)))
; __device__ __forceinline__ unsigned cvt_pk_bf16(float lo, float hi) { unsigned r; asm volatile("v_cvt_pk_bf16_f32 %0, %1, %2" : "=v"(r) : "v"(lo), "v"(hi)); return r; }
;     __device__ __forceinline__ void operator()(const f32x4 (&acc)[2][2][4][2], const Unit& u, int wr, int wc, int fr, int fq) const {
;     ...
;         for (int bj = 0; bj < 2; ++bj) {
;             const int cb = u.pn * BM + bj * HALF + wc * 32, d = cb % 192; const bool rope = d >= 128; const int j0 = ((d - 128) >> 1) + 4 * fq;
; #pragma unroll
;             for (int ai = 0; ai < 2; ++ai)
; #pragma unroll
;                 for (int m = 0; m < 4; ++m) { const int r = row0 + ai * HALF + m * 16; const float s = *(const GAS float*)(rs + r) * 0.10411754831265403f;
;                     f32x4 v0 = acc[ai][bj][m][0] * s, v1 = acc[ai][bj][m][1] * s;
;                     if (rope) { const f32x4 c4 = *(const GAS f32x4*)(cs + (size_t)r * 32 + j0), s4 = *(const GAS f32x4*)(sn + (size_t)r * 32 + j0);
;                         f32x4 a, b; a[0] = v0[0] * c4[0] - v0[1] * s4[0]; a[1] = v0[0] * s4[0] + v0[1] * c4[0]; a[2] = v0[2] * c4[1] - v0[3] * s4[1]; a[3] = v0[2] * s4[1] + v0[3] * c4[1];
;                         b[0] = v1[0] * c4[2] - v1[1] * s4[2]; b[1] = v1[0] * s4[2] + v1[1] * c4[2]; b[2] = v1[2] * c4[3] - v1[3] * s4[3]; b[3] = v1[2] * s4[3] + v1[3] * c4[3]; v0 = a; v1 = b; }
;                     u32x4 w; w.x = cvt_pk_bf16(v0[0], v0[1]); w.y = cvt_pk_bf16(v0[2], v0[3]); w.z = cvt_pk_bf16(v1[0], v1[1]); w.w = cvt_pk_bf16(v1[2], v1[3]);
;                     *(GAS u32x4*)(O + (size_t)r * QW + col0 + bj * HALF) = w; }
.LBB0_559:
	v_cvt_pk_bf16_f32 v144, v68, v69
	v_cvt_pk_bf16_f32 v145, v86, v87
	v_cvt_pk_bf16_f32 v146, v66, v67
	v_mov_b64_e32 v[66:67], s[46:47]
	s_movk_i32 s38, 0xc00
	v_mad_i64_i32 v[66:67], s[38:39], v78, s38, v[66:67]
	v_lshl_add_u64 v[66:67], v[142:143], 1, v[66:67]
	v_cvt_pk_bf16_f32 v147, v70, v71
	global_store_dwordx4 v[66:67], v[144:147], off
	v_mov_b32_e32 v68, v192
	s_bitset1_b32 s63, 7
	s_mul_hi_i32 s38, s63, 0x2aaaaaab
	s_lshr_b32 s39, s38, 31
	s_lshr_b32 s38, s38, 5
	s_add_i32 s38, s38, s39
	s_mulk_i32 s38, 0xc0
	s_sub_i32 s38, s63, s38
	s_cmpk_gt_i32 s38, 0x7f
	s_cselect_b64 s[50:51], -1, 0
	s_add_i32 s39, s38, 0xffffff80
	s_ashr_i32 s39, s39, 1
	v_or_b32_e32 v70, s39, v153
	v_ashrrev_i32_e32 v71, 31, v70
	s_cmpk_lt_i32 s38, 0x80
	v_mul_f32_e32 v78, 0x3dd53b95, v68
	v_pk_mul_f32 v[68:69], v[62:63], v[78:79] op_sel_hi:[1,0]
	v_pk_mul_f32 v[60:61], v[60:61], v[78:79] op_sel_hi:[1,0]
	v_pk_mul_f32 v[62:63], v[58:59], v[78:79] op_sel_hi:[1,0]
	v_pk_mul_f32 v[58:59], v[56:57], v[78:79] op_sel_hi:[1,0]
	v_lshlrev_b64 v[56:57], 2, v[70:71]
	s_cbranch_scc1 .LBB0_561
	v_lshl_add_u64 v[70:71], v[120:121], 0, v[56:57]
	global_load_dwordx4 v[140:143], v[70:71], off
	v_lshl_add_u64 v[70:71], v[122:123], 0, v[56:57]
	global_load_dwordx4 v[120:123], v[70:71], off
	s_waitcnt vmcnt(0)
	v_pk_mul_f32 v[78:79], v[60:61], v[140:141]
	v_pk_mul_f32 v[102:103], v[58:59], v[142:143]
	v_pk_mul_f32 v[70:71], v[60:61], v[120:121] op_sel:[1,0] op_sel_hi:[0,0]
	v_pk_fma_f32 v[60:61], v[60:61], v[140:141], v[70:71] op_sel_hi:[1,0,1]
	v_mov_b32_e32 v120, v141
	v_mul_f32_e32 v60, v69, v121
	v_pk_fma_f32 v[86:87], v[68:69], v[120:121], v[60:61] op_sel_hi:[1,1,0] neg_lo:[0,0,1] neg_hi:[0,0,1]
	v_mov_b32_e32 v140, v121
	v_mul_f32_e32 v60, v69, v141
	v_pk_fma_f32 v[94:95], v[68:69], v[140:141], v[60:61] op_sel_hi:[1,1,0]
	v_pk_mul_f32 v[68:69], v[58:59], v[122:123] op_sel:[1,0] op_sel_hi:[0,0]
	v_pk_fma_f32 v[58:59], v[58:59], v[142:143], v[68:69] op_sel_hi:[1,0,1]
	v_mov_b32_e32 v122, v143
	v_mul_f32_e32 v58, v63, v123
	v_pk_fma_f32 v[110:111], v[62:63], v[122:123], v[58:59] op_sel_hi:[1,1,0] neg_lo:[0,0,1] neg_hi:[0,0,1]
	v_mov_b32_e32 v142, v123
	v_mul_f32_e32 v58, v63, v143
	v_pk_fma_f32 v[120:121], v[62:63], v[142:143], v[58:59] op_sel_hi:[1,1,0]
	v_sub_f32_e32 v60, v78, v70
	v_sub_f32_e32 v58, v102, v68
	v_mov_b32_e32 v68, v86
	v_mov_b32_e32 v69, v94
	v_mov_b32_e32 v62, v110
	v_mov_b32_e32 v63, v120
.LBB0_561:
	v_cvt_pk_bf16_f32 v120, v60, v61
	v_cvt_pk_bf16_f32 v121, v68, v69
	v_cvt_pk_bf16_f32 v122, v58, v59
	v_cvt_pk_bf16_f32 v123, v62, v63
	global_store_dwordx4 v[124:125], v[120:123], off offset:256
	v_mov_b32_e32 v58, v193
	v_cndmask_b32_e64 v59, 0, 1, s[50:51]
	v_cmp_ne_u32_e64 s[38:39], 1, v59
	s_andn2_b64 vcc, exec, s[50:51]
	v_mul_f32_e32 v58, 0x3dd53b95, v58
	v_pk_mul_f32 v[54:55], v[54:55], v[58:59] op_sel_hi:[1,0]
	v_pk_mul_f32 v[52:53], v[52:53], v[58:59] op_sel_hi:[1,0]
	v_pk_mul_f32 v[50:51], v[50:51], v[58:59] op_sel_hi:[1,0]
	v_pk_mul_f32 v[48:49], v[48:49], v[58:59] op_sel_hi:[1,0]
	s_cbranch_vccnz .LBB0_563
	v_lshl_add_u64 v[58:59], v[112:113], 0, v[56:57]
	v_lshl_add_u64 v[62:63], v[114:115], 0, v[56:57]
	global_load_dwordx4 v[58:61], v[58:59], off
	s_nop 0
	global_load_dwordx4 v[68:71], v[62:63], off
	s_waitcnt vmcnt(0)
	v_pk_mul_f32 v[78:79], v[52:53], v[58:59]
	v_pk_mul_f32 v[62:63], v[52:53], v[68:69] op_sel:[1,0] op_sel_hi:[0,0]
	v_pk_fma_f32 v[52:53], v[52:53], v[58:59], v[62:63] op_sel_hi:[1,0,1]
	v_mov_b32_e32 v68, v59
	v_mul_f32_e32 v52, v55, v69
	v_pk_fma_f32 v[86:87], v[54:55], v[68:69], v[52:53] op_sel_hi:[1,1,0] neg_lo:[0,0,1] neg_hi:[0,0,1]
	v_mov_b32_e32 v58, v69
	v_mul_f32_e32 v52, v55, v59
	v_pk_fma_f32 v[58:59], v[54:55], v[58:59], v[52:53] op_sel_hi:[1,1,0]
	v_pk_mul_f32 v[54:55], v[48:49], v[70:71] op_sel:[1,0] op_sel_hi:[0,0]
	v_pk_mul_f32 v[68:69], v[48:49], v[60:61]
	v_pk_fma_f32 v[48:49], v[48:49], v[60:61], v[54:55] op_sel_hi:[1,0,1]
	v_mov_b32_e32 v70, v61
	v_mul_f32_e32 v48, v51, v71
	v_pk_fma_f32 v[94:95], v[50:51], v[70:71], v[48:49] op_sel_hi:[1,1,0] neg_lo:[0,0,1] neg_hi:[0,0,1]
	v_mov_b32_e32 v60, v71
	v_mul_f32_e32 v48, v51, v61
	v_pk_fma_f32 v[60:61], v[50:51], v[60:61], v[48:49] op_sel_hi:[1,1,0]
	v_sub_f32_e32 v52, v78, v62
	v_sub_f32_e32 v48, v68, v54
	v_mov_b32_e32 v54, v86
	v_mov_b32_e32 v55, v58
	v_mov_b32_e32 v50, v94
	v_mov_b32_e32 v51, v60
.LBB0_563:
	v_cvt_pk_bf16_f32 v52, v52, v53
	v_cvt_pk_bf16_f32 v53, v54, v55
	v_cvt_pk_bf16_f32 v54, v48, v49
	v_cvt_pk_bf16_f32 v55, v50, v51
	global_store_dwordx4 v[118:119], v[52:55], off offset:256
	v_mov_b32_e32 v48, v194
	s_and_b64 vcc, exec, s[38:39]
	v_mul_f32_e32 v48, 0x3dd53b95, v48
	v_pk_mul_f32 v[46:47], v[46:47], v[48:49] op_sel_hi:[1,0]
	v_pk_mul_f32 v[44:45], v[44:45], v[48:49] op_sel_hi:[1,0]
	v_pk_mul_f32 v[42:43], v[42:43], v[48:49] op_sel_hi:[1,0]
	v_pk_mul_f32 v[40:41], v[40:41], v[48:49] op_sel_hi:[1,0]
	s_cbranch_vccnz .LBB0_565
	v_lshl_add_u64 v[48:49], v[116:117], 0, v[56:57]
	v_lshl_add_u64 v[52:53], v[104:105], 0, v[56:57]
	global_load_dwordx4 v[48:51], v[48:49], off
	s_nop 0
	global_load_dwordx4 v[52:55], v[52:53], off
	s_waitcnt vmcnt(0)
	v_pk_mul_f32 v[60:61], v[44:45], v[48:49]
	v_pk_mul_f32 v[58:59], v[44:45], v[52:53] op_sel:[1,0] op_sel_hi:[0,0]
	v_pk_fma_f32 v[44:45], v[44:45], v[48:49], v[58:59] op_sel_hi:[1,0,1]
	v_mov_b32_e32 v52, v49
	v_mul_f32_e32 v44, v47, v53
	v_pk_fma_f32 v[62:63], v[46:47], v[52:53], v[44:45] op_sel_hi:[1,1,0] neg_lo:[0,0,1] neg_hi:[0,0,1]
	v_mov_b32_e32 v48, v53
	v_mul_f32_e32 v44, v47, v49
	v_pk_fma_f32 v[48:49], v[46:47], v[48:49], v[44:45] op_sel_hi:[1,1,0]
	v_pk_mul_f32 v[46:47], v[40:41], v[54:55] op_sel:[1,0] op_sel_hi:[0,0]
	v_pk_mul_f32 v[52:53], v[40:41], v[50:51]
	v_pk_fma_f32 v[40:41], v[40:41], v[50:51], v[46:47] op_sel_hi:[1,0,1]
	v_mov_b32_e32 v54, v51
	v_mul_f32_e32 v40, v43, v55
	v_pk_fma_f32 v[68:69], v[42:43], v[54:55], v[40:41] op_sel_hi:[1,1,0] neg_lo:[0,0,1] neg_hi:[0,0,1]
	v_mov_b32_e32 v50, v55
	v_mul_f32_e32 v40, v43, v51
	v_pk_fma_f32 v[50:51], v[42:43], v[50:51], v[40:41] op_sel_hi:[1,1,0]
	v_sub_f32_e32 v44, v60, v58
	v_sub_f32_e32 v40, v52, v46
	v_mov_b32_e32 v46, v62
	v_mov_b32_e32 v47, v48
	v_mov_b32_e32 v42, v68
	v_mov_b32_e32 v43, v50
; #define GAS __attribute__((address_space(1)))
; __device__ __forceinline__ unsigned cvt_pk_bf16(float lo, float hi) { unsigned r; asm volatile("v_cvt_pk_bf16_f32 %0, %1, %2" : "=v"(r) : "v"(lo), "v"(hi)); return r; }
;     __device__ __forceinline__ void operator()(const f32x4 (&acc)[2][2][4][2], const Unit& u, int wr, int wc, int fr, int fq) const {
;     ...
;                 for (int m = 0; m < 4; ++m) { const int r = row0 + ai * HALF + m * 16; const float s = *(const GAS float*)(rs + r) * 0.10411754831265403f;
;                     f32x4 v0 = acc[ai][bj][m][0] * s, v1 = acc[ai][bj][m][1] * s;
;                     if (rope) { const f32x4 c4 = *(const GAS f32x4*)(cs + (size_t)r * 32 + j0), s4 = *(const GAS f32x4*)(sn + (size_t)r * 32 + j0);
;                         f32x4 a, b; a[0] = v0[0] * c4[0] - v0[1] * s4[0]; a[1] = v0[0] * s4[0] + v0[1] * c4[0]; a[2] = v0[2] * c4[1] - v0[3] * s4[1]; a[3] = v0[2] * s4[1] + v0[3] * c4[1];
;                         b[0] = v1[0] * c4[2] - v1[1] * s4[2]; b[1] = v1[0] * s4[2] + v1[1] * c4[2]; b[2] = v1[2] * c4[3] - v1[3] * s4[3]; b[3] = v1[2] * s4[3] + v1[3] * c4[3]; v0 = a; v1 = b; }
;                     u32x4 w; w.x = cvt_pk_bf16(v0[0], v0[1]); w.y = cvt_pk_bf16(v0[2], v0[3]); w.z = cvt_pk_bf16(v1[0], v1[1]); w.w = cvt_pk_bf16(v1[2], v1[3]);
;                     *(GAS u32x4*)(O + (size_t)r * QW + col0 + bj * HALF) = w; }
.LBB0_565:
	v_cvt_pk_bf16_f32 v44, v44, v45
	v_cvt_pk_bf16_f32 v45, v46, v47
	v_cvt_pk_bf16_f32 v46, v40, v41
	v_cvt_pk_bf16_f32 v47, v42, v43
	global_store_dwordx4 v[108:109], v[44:47], off offset:256
	v_mov_b32_e32 v40, v195
	s_and_b64 vcc, exec, s[38:39]
	v_mul_f32_e32 v40, 0x3dd53b95, v40
	v_pk_mul_f32 v[38:39], v[38:39], v[40:41] op_sel_hi:[1,0]
	v_pk_mul_f32 v[36:37], v[36:37], v[40:41] op_sel_hi:[1,0]
	v_pk_mul_f32 v[34:35], v[34:35], v[40:41] op_sel_hi:[1,0]
	v_pk_mul_f32 v[32:33], v[32:33], v[40:41] op_sel_hi:[1,0]
	s_cbranch_vccnz .LBB0_567
	v_lshl_add_u64 v[40:41], v[106:107], 0, v[56:57]
	v_lshl_add_u64 v[44:45], v[96:97], 0, v[56:57]
	global_load_dwordx4 v[40:43], v[40:41], off
	s_nop 0
	global_load_dwordx4 v[44:47], v[44:45], off
	s_waitcnt vmcnt(0)
	v_pk_mul_f32 v[50:51], v[36:37], v[40:41]
	v_pk_mul_f32 v[48:49], v[36:37], v[44:45] op_sel:[1,0] op_sel_hi:[0,0]
	v_pk_fma_f32 v[36:37], v[36:37], v[40:41], v[48:49] op_sel_hi:[1,0,1]
	v_mov_b32_e32 v44, v41
	v_mul_f32_e32 v36, v39, v45
	v_pk_fma_f32 v[52:53], v[38:39], v[44:45], v[36:37] op_sel_hi:[1,1,0] neg_lo:[0,0,1] neg_hi:[0,0,1]
	v_mov_b32_e32 v40, v45
	v_mul_f32_e32 v36, v39, v41
	v_pk_fma_f32 v[40:41], v[38:39], v[40:41], v[36:37] op_sel_hi:[1,1,0]
	v_pk_mul_f32 v[38:39], v[32:33], v[46:47] op_sel:[1,0] op_sel_hi:[0,0]
	v_pk_mul_f32 v[44:45], v[32:33], v[42:43]
	v_pk_fma_f32 v[32:33], v[32:33], v[42:43], v[38:39] op_sel_hi:[1,0,1]
	v_mov_b32_e32 v46, v43
	v_mul_f32_e32 v32, v35, v47
	v_pk_fma_f32 v[54:55], v[34:35], v[46:47], v[32:33] op_sel_hi:[1,1,0] neg_lo:[0,0,1] neg_hi:[0,0,1]
	v_mov_b32_e32 v42, v47
	v_mul_f32_e32 v32, v35, v43
	v_pk_fma_f32 v[42:43], v[34:35], v[42:43], v[32:33] op_sel_hi:[1,1,0]
	v_sub_f32_e32 v36, v50, v48
	v_sub_f32_e32 v32, v44, v38
	v_mov_b32_e32 v38, v52
	v_mov_b32_e32 v39, v40
	v_mov_b32_e32 v34, v54
	v_mov_b32_e32 v35, v42
.LBB0_567:
	v_cvt_pk_bf16_f32 v36, v36, v37
	v_cvt_pk_bf16_f32 v37, v38, v39
	v_cvt_pk_bf16_f32 v38, v32, v33
	v_cvt_pk_bf16_f32 v39, v34, v35
	global_store_dwordx4 v[100:101], v[36:39], off offset:256
	v_mov_b32_e32 v32, v196
	s_and_b64 vcc, exec, s[38:39]
	v_mul_f32_e32 v32, 0x3dd53b95, v32
	v_pk_mul_f32 v[30:31], v[30:31], v[32:33] op_sel_hi:[1,0]
	v_pk_mul_f32 v[28:29], v[28:29], v[32:33] op_sel_hi:[1,0]
	v_pk_mul_f32 v[26:27], v[26:27], v[32:33] op_sel_hi:[1,0]
	v_pk_mul_f32 v[24:25], v[24:25], v[32:33] op_sel_hi:[1,0]
	s_cbranch_vccnz .LBB0_569
	v_lshl_add_u64 v[32:33], v[98:99], 0, v[56:57]
	v_lshl_add_u64 v[36:37], v[88:89], 0, v[56:57]
	global_load_dwordx4 v[32:35], v[32:33], off
	s_nop 0
	global_load_dwordx4 v[36:39], v[36:37], off
	s_waitcnt vmcnt(0)
	v_pk_mul_f32 v[42:43], v[28:29], v[32:33]
	v_pk_mul_f32 v[40:41], v[28:29], v[36:37] op_sel:[1,0] op_sel_hi:[0,0]
	v_pk_fma_f32 v[28:29], v[28:29], v[32:33], v[40:41] op_sel_hi:[1,0,1]
	v_mov_b32_e32 v36, v33
	v_mul_f32_e32 v28, v31, v37
	v_pk_fma_f32 v[44:45], v[30:31], v[36:37], v[28:29] op_sel_hi:[1,1,0] neg_lo:[0,0,1] neg_hi:[0,0,1]
	v_mov_b32_e32 v32, v37
	v_mul_f32_e32 v28, v31, v33
	v_pk_fma_f32 v[32:33], v[30:31], v[32:33], v[28:29] op_sel_hi:[1,1,0]
	v_pk_mul_f32 v[30:31], v[24:25], v[38:39] op_sel:[1,0] op_sel_hi:[0,0]
	v_pk_mul_f32 v[36:37], v[24:25], v[34:35]
	v_pk_fma_f32 v[24:25], v[24:25], v[34:35], v[30:31] op_sel_hi:[1,0,1]
	v_mov_b32_e32 v38, v35
	v_mul_f32_e32 v24, v27, v39
	v_pk_fma_f32 v[46:47], v[26:27], v[38:39], v[24:25] op_sel_hi:[1,1,0] neg_lo:[0,0,1] neg_hi:[0,0,1]
	v_mov_b32_e32 v34, v39
	v_mul_f32_e32 v24, v27, v35
	v_pk_fma_f32 v[34:35], v[26:27], v[34:35], v[24:25] op_sel_hi:[1,1,0]
	v_sub_f32_e32 v28, v42, v40
	v_sub_f32_e32 v24, v36, v30
	v_mov_b32_e32 v30, v44
	v_mov_b32_e32 v31, v32
	v_mov_b32_e32 v26, v46
	v_mov_b32_e32 v27, v34
; #define GAS __attribute__((address_space(1)))
; __device__ __forceinline__ unsigned cvt_pk_bf16(float lo, float hi) { unsigned r; asm volatile("v_cvt_pk_bf16_f32 %0, %1, %2" : "=v"(r) : "v"(lo), "v"(hi)); return r; }
;     __device__ __forceinline__ void operator()(const f32x4 (&acc)[2][2][4][2], const Unit& u, int wr, int wc, int fr, int fq) const {
;     ...
;                 for (int m = 0; m < 4; ++m) { const int r = row0 + ai * HALF + m * 16; const float s = *(const GAS float*)(rs + r) * 0.10411754831265403f;
;                     f32x4 v0 = acc[ai][bj][m][0] * s, v1 = acc[ai][bj][m][1] * s;
;                     if (rope) { const f32x4 c4 = *(const GAS f32x4*)(cs + (size_t)r * 32 + j0), s4 = *(const GAS f32x4*)(sn + (size_t)r * 32 + j0);
;                         f32x4 a, b; a[0] = v0[0] * c4[0] - v0[1] * s4[0]; a[1] = v0[0] * s4[0] + v0[1] * c4[0]; a[2] = v0[2] * c4[1] - v0[3] * s4[1]; a[3] = v0[2] * s4[1] + v0[3] * c4[1];
;                         b[0] = v1[0] * c4[2] - v1[1] * s4[2]; b[1] = v1[0] * s4[2] + v1[1] * c4[2]; b[2] = v1[2] * c4[3] - v1[3] * s4[3]; b[3] = v1[2] * s4[3] + v1[3] * c4[3]; v0 = a; v1 = b; }
;                     u32x4 w; w.x = cvt_pk_bf16(v0[0], v0[1]); w.y = cvt_pk_bf16(v0[2], v0[3]); w.z = cvt_pk_bf16(v1[0], v1[1]); w.w = cvt_pk_bf16(v1[2], v1[3]);
;                     *(GAS u32x4*)(O + (size_t)r * QW + col0 + bj * HALF) = w; }
.LBB0_569:
	v_cvt_pk_bf16_f32 v28, v28, v29
	v_cvt_pk_bf16_f32 v29, v30, v31
	v_cvt_pk_bf16_f32 v30, v24, v25
	v_cvt_pk_bf16_f32 v31, v26, v27
	global_store_dwordx4 v[92:93], v[28:31], off offset:256
	v_mov_b32_e32 v24, v197
	s_and_b64 vcc, exec, s[38:39]
	v_mul_f32_e32 v24, 0x3dd53b95, v24
	v_pk_mul_f32 v[22:23], v[22:23], v[24:25] op_sel_hi:[1,0]
	v_pk_mul_f32 v[20:21], v[20:21], v[24:25] op_sel_hi:[1,0]
	v_pk_mul_f32 v[18:19], v[18:19], v[24:25] op_sel_hi:[1,0]
	v_pk_mul_f32 v[16:17], v[16:17], v[24:25] op_sel_hi:[1,0]
	s_cbranch_vccnz .LBB0_571
	v_lshl_add_u64 v[24:25], v[90:91], 0, v[56:57]
	v_lshl_add_u64 v[28:29], v[80:81], 0, v[56:57]
	global_load_dwordx4 v[24:27], v[24:25], off
	s_nop 0
	global_load_dwordx4 v[28:31], v[28:29], off
	s_waitcnt vmcnt(0)
	v_pk_mul_f32 v[34:35], v[20:21], v[24:25]
	v_pk_mul_f32 v[32:33], v[20:21], v[28:29] op_sel:[1,0] op_sel_hi:[0,0]
	v_pk_fma_f32 v[20:21], v[20:21], v[24:25], v[32:33] op_sel_hi:[1,0,1]
	v_mov_b32_e32 v28, v25
	v_mul_f32_e32 v20, v23, v29
	v_pk_fma_f32 v[36:37], v[22:23], v[28:29], v[20:21] op_sel_hi:[1,1,0] neg_lo:[0,0,1] neg_hi:[0,0,1]
	v_mov_b32_e32 v24, v29
	v_mul_f32_e32 v20, v23, v25
	v_pk_fma_f32 v[24:25], v[22:23], v[24:25], v[20:21] op_sel_hi:[1,1,0]
	v_pk_mul_f32 v[22:23], v[16:17], v[30:31] op_sel:[1,0] op_sel_hi:[0,0]
	v_pk_mul_f32 v[28:29], v[16:17], v[26:27]
	v_pk_fma_f32 v[16:17], v[16:17], v[26:27], v[22:23] op_sel_hi:[1,0,1]
	v_mov_b32_e32 v30, v27
	v_mul_f32_e32 v16, v19, v31
	v_pk_fma_f32 v[38:39], v[18:19], v[30:31], v[16:17] op_sel_hi:[1,1,0] neg_lo:[0,0,1] neg_hi:[0,0,1]
	v_mov_b32_e32 v26, v31
	v_mul_f32_e32 v16, v19, v27
	v_pk_fma_f32 v[26:27], v[18:19], v[26:27], v[16:17] op_sel_hi:[1,1,0]
	v_sub_f32_e32 v20, v34, v32
	v_sub_f32_e32 v16, v28, v22
	v_mov_b32_e32 v22, v36
	v_mov_b32_e32 v23, v24
	v_mov_b32_e32 v18, v38
	v_mov_b32_e32 v19, v26
.LBB0_571:
	v_cvt_pk_bf16_f32 v20, v20, v21
	v_cvt_pk_bf16_f32 v21, v22, v23
	v_cvt_pk_bf16_f32 v22, v16, v17
	v_cvt_pk_bf16_f32 v23, v18, v19
	global_store_dwordx4 v[84:85], v[20:23], off offset:256
	v_mov_b32_e32 v16, v198
	s_and_b64 vcc, exec, s[38:39]
	v_mul_f32_e32 v16, 0x3dd53b95, v16
	v_pk_mul_f32 v[14:15], v[14:15], v[16:17] op_sel_hi:[1,0]
	v_pk_mul_f32 v[12:13], v[12:13], v[16:17] op_sel_hi:[1,0]
	v_pk_mul_f32 v[10:11], v[10:11], v[16:17] op_sel_hi:[1,0]
	v_pk_mul_f32 v[8:9], v[8:9], v[16:17] op_sel_hi:[1,0]
	s_cbranch_vccnz .LBB0_573
	v_lshl_add_u64 v[16:17], v[82:83], 0, v[56:57]
	v_lshl_add_u64 v[20:21], v[72:73], 0, v[56:57]
	global_load_dwordx4 v[16:19], v[16:17], off
	s_nop 0
	global_load_dwordx4 v[20:23], v[20:21], off
	s_waitcnt vmcnt(0)
	v_pk_mul_f32 v[26:27], v[12:13], v[16:17]
	v_pk_mul_f32 v[24:25], v[12:13], v[20:21] op_sel:[1,0] op_sel_hi:[0,0]
	v_pk_fma_f32 v[12:13], v[12:13], v[16:17], v[24:25] op_sel_hi:[1,0,1]
	v_mov_b32_e32 v20, v17
	v_mul_f32_e32 v12, v15, v21
	v_pk_fma_f32 v[28:29], v[14:15], v[20:21], v[12:13] op_sel_hi:[1,1,0] neg_lo:[0,0,1] neg_hi:[0,0,1]
	v_mov_b32_e32 v16, v21
	v_mul_f32_e32 v12, v15, v17
	v_pk_fma_f32 v[16:17], v[14:15], v[16:17], v[12:13] op_sel_hi:[1,1,0]
	v_pk_mul_f32 v[14:15], v[8:9], v[22:23] op_sel:[1,0] op_sel_hi:[0,0]
	v_pk_mul_f32 v[20:21], v[8:9], v[18:19]
	v_pk_fma_f32 v[8:9], v[8:9], v[18:19], v[14:15] op_sel_hi:[1,0,1]
	v_mov_b32_e32 v22, v19
	v_mul_f32_e32 v8, v11, v23
	v_pk_fma_f32 v[30:31], v[10:11], v[22:23], v[8:9] op_sel_hi:[1,1,0] neg_lo:[0,0,1] neg_hi:[0,0,1]
	v_mov_b32_e32 v18, v23
	v_mul_f32_e32 v8, v11, v19
	v_pk_fma_f32 v[18:19], v[10:11], v[18:19], v[8:9] op_sel_hi:[1,1,0]
	v_sub_f32_e32 v12, v26, v24
	v_sub_f32_e32 v8, v20, v14
	v_mov_b32_e32 v14, v28
	v_mov_b32_e32 v15, v16
	v_mov_b32_e32 v10, v30
	v_mov_b32_e32 v11, v18
.LBB0_573:
	v_cvt_pk_bf16_f32 v12, v12, v13
	v_cvt_pk_bf16_f32 v13, v14, v15
	v_cvt_pk_bf16_f32 v14, v8, v9
	v_cvt_pk_bf16_f32 v15, v10, v11
	global_store_dwordx4 v[76:77], v[12:15], off offset:256
	v_mov_b32_e32 v8, v199
	s_and_b64 vcc, exec, s[38:39]
	v_mul_f32_e32 v8, 0x3dd53b95, v8
	v_pk_mul_f32 v[6:7], v[6:7], v[8:9] op_sel_hi:[1,0]
	v_pk_mul_f32 v[4:5], v[4:5], v[8:9] op_sel_hi:[1,0]
	v_pk_mul_f32 v[2:3], v[2:3], v[8:9] op_sel_hi:[1,0]
	v_pk_mul_f32 v[0:1], v[0:1], v[8:9] op_sel_hi:[1,0]
	s_cbranch_vccnz .LBB0_575
	v_lshl_add_u64 v[8:9], v[74:75], 0, v[56:57]
	v_lshl_add_u64 v[12:13], v[64:65], 0, v[56:57]
	global_load_dwordx4 v[8:11], v[8:9], off
	s_nop 0
	global_load_dwordx4 v[12:15], v[12:13], off
	s_waitcnt vmcnt(0)
	v_pk_mul_f32 v[18:19], v[4:5], v[8:9]
	v_pk_mul_f32 v[16:17], v[4:5], v[12:13] op_sel:[1,0] op_sel_hi:[0,0]
	v_pk_fma_f32 v[4:5], v[4:5], v[8:9], v[16:17] op_sel_hi:[1,0,1]
	v_mov_b32_e32 v12, v9
	v_mul_f32_e32 v4, v7, v13
	v_pk_fma_f32 v[20:21], v[6:7], v[12:13], v[4:5] op_sel_hi:[1,1,0] neg_lo:[0,0,1] neg_hi:[0,0,1]
	v_mov_b32_e32 v8, v13
	v_mul_f32_e32 v4, v7, v9
	v_pk_fma_f32 v[8:9], v[6:7], v[8:9], v[4:5] op_sel_hi:[1,1,0]
	v_pk_mul_f32 v[6:7], v[0:1], v[14:15] op_sel:[1,0] op_sel_hi:[0,0]
	v_pk_mul_f32 v[12:13], v[0:1], v[10:11]
	v_pk_fma_f32 v[0:1], v[0:1], v[10:11], v[6:7] op_sel_hi:[1,0,1]
	v_mov_b32_e32 v14, v11
	v_mul_f32_e32 v0, v3, v15
	v_pk_fma_f32 v[22:23], v[2:3], v[14:15], v[0:1] op_sel_hi:[1,1,0] neg_lo:[0,0,1] neg_hi:[0,0,1]
	v_mov_b32_e32 v10, v15
	v_mul_f32_e32 v0, v3, v11
	v_pk_fma_f32 v[10:11], v[2:3], v[10:11], v[0:1] op_sel_hi:[1,1,0]
	v_sub_f32_e32 v4, v18, v16
	v_sub_f32_e32 v0, v12, v6
	v_mov_b32_e32 v6, v20
	v_mov_b32_e32 v7, v8
	v_mov_b32_e32 v2, v22
	v_mov_b32_e32 v3, v10
